# PB item heads: removed conservative vmcnt(0) (ssd_pass1 first-load round trip, previous item's store drain)
# speedup vs baseline: 1.0118x; 1.0118x over previous
.LBB0_401:
	s_cmpk_gt_i32 s15, 0xff
	s_mov_b64 s[0:1], -1
	s_cbranch_scc0 .LBB0_407
	s_and_b32 s10, s15, 3
	s_and_b32 s9, s15, 4
	v_mov_b32_e32 v28, v167
	s_lshl_b32 s11, s10, 3
	s_or_b32 s9, s11, s9
	v_ashrrev_i32_e32 v5, 7, v28
	v_add_u32_e32 v0, s9, v5
	s_waitcnt lgkmcnt(0)
	v_ashrrev_i32_e32 v1, 31, v0
	v_readlane_b32 s16, v252, 1
	s_lshl_b32 s0, s14, 5
	s_add_i32 s8, s15, 0xffffff00
	v_lshlrev_b64 v[0:1], 15, v[0:1]
	v_readlane_b32 s17, v252, 2
	s_and_b32 s22, s13, 3
	s_bfe_u32 s11, s15, 0x10002
	s_and_b32 s28, s0, 0xffffff00
	s_lshr_b32 s8, s8, 3
	v_lshl_add_u64 v[0:1], s[16:17], 0, v[0:1]
	s_mul_i32 s16, s22, 0x408000
	s_mul_i32 s11, s11, 0x204000
	s_lshl_b64 s[0:1], s[28:29], 1
	s_lshl_b32 s28, s8, 8
	v_lshlrev_b32_e32 v4, 3, v28
	s_add_i32 s16, s16, s11
	v_readfirstlane_b32 s11, v28
	v_lshl_add_u64 v[0:1], s[28:29], 2, v[0:1]
	v_and_b32_e32 v2, 0x3f8, v4
	v_mov_b32_e32 v3, v157
	s_mul_i32 s20, s10, 0x204000
	v_ashrrev_i32_e32 v26, 3, v28
	s_lshl_b32 s23, s16, 1
	s_ashr_i32 s10, s11, 7
	s_mul_i32 s16, s9, 0x102000
	s_movk_i32 s18, 0x48
	v_lshl_add_u64 v[0:1], v[0:1], 0, v[2:3]
	v_mul_lo_u32 v29, v26, s18
	s_add_u32 s18, s82, s16
	global_load_dwordx2 v[24:25], v[0:1], off
	v_and_b32_e32 v0, 56, v4
	v_lshlrev_b32_e32 v1, 10, v5
	v_readlane_b32 s16, v253, 63
	s_addc_u32 s19, s83, 0
	v_readlane_b32 s34, v251, 32
	v_add_u32_e32 v14, 64, v26
	v_add_u32_e32 v6, 0x80, v26
	v_add_u32_e32 v8, 0xc0, v26
	v_lshlrev_b32_e32 v156, 1, v0
	v_add3_u32 v30, s16, v1, v2
	s_movk_i32 s25, 0x90
	v_readlane_b32 s35, v251, 33
	s_add_u32 s20, s34, s20
	v_mov_b64_e32 v[0:1], s[18:19]
	s_mov_b32 s17, s29
	v_mul_lo_u32 v109, v6, s25
	s_addc_u32 s21, s35, 0
	v_mad_i64_i32 v[2:3], s[18:19], v26, s37, v[0:1]
	s_lshl_b32 s16, s8, 9
	v_mad_i64_i32 v[4:5], s[18:19], v14, s37, v[0:1]
	v_mad_i64_i32 v[6:7], s[18:19], v6, s37, v[0:1]
	v_mad_i64_i32 v[0:1], s[18:19], v8, s37, v[0:1]
	v_lshl_add_u64 v[2:3], v[2:3], 0, s[16:17]
	v_lshl_add_u64 v[4:5], v[4:5], 0, s[16:17]
	v_lshl_add_u64 v[6:7], v[6:7], 0, s[16:17]
	v_lshl_add_u64 v[0:1], v[0:1], 0, s[16:17]
	v_mov_b64_e32 v[8:9], s[20:21]
	v_lshl_add_u64 v[2:3], v[2:3], 0, v[156:157]
	v_lshl_add_u64 v[4:5], v[4:5], 0, v[156:157]
	v_lshl_add_u64 v[10:11], v[6:7], 0, v[156:157]
	v_lshl_add_u64 v[12:13], v[0:1], 0, v[156:157]
	v_mad_i64_i32 v[16:17], s[18:19], v26, s37, v[8:9]
	v_mad_i64_i32 v[18:19], s[18:19], v14, s37, v[8:9]
	global_load_dwordx4 v[0:3], v[2:3], off
	s_nop 0
	global_load_dwordx4 v[4:7], v[4:5], off
	s_nop 0
	global_load_dwordx4 v[8:11], v[10:11], off
	s_nop 0
	global_load_dwordx4 v[12:15], v[12:13], off
	v_lshl_add_u64 v[16:17], v[16:17], 0, s[16:17]
	v_lshl_add_u64 v[18:19], v[18:19], 0, s[16:17]
	v_lshl_add_u64 v[16:17], v[16:17], 0, v[156:157]
	v_lshl_add_u64 v[20:21], v[18:19], 0, v[156:157]
	global_load_dwordx4 v[16:19], v[16:17], off
	s_nop 0
	global_load_dwordx4 v[20:23], v[20:21], off
	s_lshl_b32 s24, s10, 10
	v_bfe_u32 v27, v28, 4, 2
	s_add_i32 s16, s24, 16
	v_lshl_add_u32 v118, v27, 5, s16
	v_and_b32_e32 v114, 15, v28
	v_lshlrev_b32_e32 v108, 3, v27
	s_and_b32 s11, s11, 64
	v_lshlrev_b32_e32 v28, 4, v28
	v_and_b32_e32 v28, 0x70, v28
	v_lshl_or_b32 v31, s10, 6, v114
	v_or_b32_e32 v32, s11, v114
	v_mov_b32_e32 v36, 0
	v_add_u32_e32 v115, 0x2400, v109
	v_mul_lo_u32 v116, v31, s25
	v_mul_u32_u24_e32 v117, 0x90, v32
	v_lshlrev_b32_e32 v119, 1, v29
	v_mov_b32_e32 v37, v36
	v_mov_b32_e32 v38, v36
	v_mov_b32_e32 v39, v36
	v_mov_b32_e32 v52, v36
	v_mov_b32_e32 v53, v36
	v_mov_b32_e32 v54, v36
	v_mov_b32_e32 v55, v36
	v_mov_b32_e32 v72, v36
	v_mov_b32_e32 v73, v36
	v_mov_b32_e32 v74, v36
	v_mov_b32_e32 v75, v36
	v_mov_b32_e32 v56, v36
	v_mov_b32_e32 v57, v36
	v_mov_b32_e32 v58, v36
	v_mov_b32_e32 v59, v36
	v_mov_b32_e32 v32, v36
	v_mov_b32_e32 v33, v36
	v_mov_b32_e32 v34, v36
	s_waitcnt vmcnt(0)
	ds_write_b64 v30, v[24:25]
	v_mad_i64_i32 v[24:25], s[16:17], v26, s37, 0
	v_mad_u64_u32 v[26:27], s[16:17], s22, v200, v[24:25]
	s_add_u32 s16, s4, s23
	v_or_b32_e32 v26, v26, v28
	v_or_b32_e32 v24, v24, v28
	s_addc_u32 s17, s5, 0
	v_lshl_add_u64 v[110:111], s[4:5], 0, v[26:27]
	v_lshl_add_u64 v[112:113], s[16:17], 0, v[24:25]
	s_mov_b32 s16, 0
	s_movk_i32 s17, 0xfc00
	v_mov_b32_e32 v35, v36
	v_mov_b32_e32 v48, v36
	v_mov_b32_e32 v49, v36
	v_mov_b32_e32 v50, v36
	v_mov_b32_e32 v51, v36
	v_mov_b32_e32 v68, v36
	v_mov_b32_e32 v69, v36
	v_mov_b32_e32 v70, v36
	v_mov_b32_e32 v71, v36
	v_mov_b32_e32 v76, v36
	v_mov_b32_e32 v77, v36
	v_mov_b32_e32 v78, v36
	v_mov_b32_e32 v79, v36
	v_mov_b32_e32 v28, v36
	v_mov_b32_e32 v29, v36
	v_mov_b32_e32 v30, v36
	v_mov_b32_e32 v31, v36
	v_mov_b32_e32 v44, v36
	v_mov_b32_e32 v45, v36
	v_mov_b32_e32 v46, v36
	v_mov_b32_e32 v47, v36
	v_mov_b32_e32 v64, v36
	v_mov_b32_e32 v65, v36
	v_mov_b32_e32 v66, v36
	v_mov_b32_e32 v67, v36
	v_mov_b32_e32 v84, v36
	v_mov_b32_e32 v85, v36
	v_mov_b32_e32 v86, v36
	v_mov_b32_e32 v87, v36
	v_mov_b32_e32 v24, v36
	v_mov_b32_e32 v25, v36
	v_mov_b32_e32 v26, v36
	v_mov_b32_e32 v27, v36
	v_mov_b32_e32 v40, v36
	v_mov_b32_e32 v41, v36
	v_mov_b32_e32 v42, v36
	v_mov_b32_e32 v43, v36
	v_mov_b32_e32 v60, v36
	v_mov_b32_e32 v61, v36
	v_mov_b32_e32 v62, v36
	v_mov_b32_e32 v63, v36
	v_mov_b32_e32 v80, v36
	v_mov_b32_e32 v81, v36
	v_mov_b32_e32 v82, v36
	v_mov_b32_e32 v83, v36
	s_branch .LBB0_404

.LBB0_407:
	s_and_b64 vcc, exec, s[0:1]
	s_cbranch_vccz .LBB0_400
	s_and_b32 s16, s15, 7
	s_ashr_i32 s17, s15, 3
	s_lshl_b32 s8, s17, 8
	s_mul_i32 s10, s16, 0x204000
	s_ashr_i32 s9, s8, 31
	s_lshl_b32 s0, s10, 1
	s_add_u32 s0, s78, s0
	s_addc_u32 s1, s79, 0
	v_mov_b32_e32 v100, v167
	s_add_u32 s10, s64, s10
	s_addc_u32 s11, s65, 0
	v_ashrrev_i32_e32 v24, 3, v100
	v_lshlrev_b32_e32 v0, 3, v100
	v_mov_b64_e32 v[8:9], s[0:1]
	v_and_b32_e32 v2, 56, v0
	s_waitcnt lgkmcnt(0)
	v_mad_i64_i32 v[0:1], s[0:1], v24, s37, v[8:9]
	v_add_u32_e32 v20, 64, v24
	v_add_u32_e32 v25, 0x80, v24
	v_add_u32_e32 v12, 0xc0, v24
	v_mov_b64_e32 v[16:17], s[10:11]
	s_lshl_b64 s[0:1], s[8:9], 1
	v_lshlrev_b32_e32 v156, 1, v2
	v_mad_i64_i32 v[2:3], s[18:19], v20, s37, v[8:9]
	v_mad_i64_i32 v[10:11], s[18:19], v25, s37, v[8:9]
	v_mad_i64_i32 v[8:9], s[18:19], v12, s37, v[8:9]
	v_mad_i64_i32 v[18:19], s[10:11], v24, s37, v[16:17]
	v_mad_i64_i32 v[16:17], s[10:11], v20, s37, v[16:17]
	v_lshl_add_u64 v[0:1], v[0:1], 0, s[0:1]
	v_lshl_add_u64 v[2:3], v[2:3], 0, s[0:1]
	v_lshl_add_u64 v[10:11], v[10:11], 0, s[0:1]
	v_lshl_add_u64 v[8:9], v[8:9], 0, s[0:1]
	v_lshl_add_u64 v[18:19], v[18:19], 0, s[0:1]
	v_lshl_add_u64 v[16:17], v[16:17], 0, s[0:1]
	v_lshl_add_u64 v[0:1], v[0:1], 0, v[156:157]
	v_lshl_add_u64 v[4:5], v[2:3], 0, v[156:157]
	v_lshl_add_u64 v[10:11], v[10:11], 0, v[156:157]
	v_lshl_add_u64 v[12:13], v[8:9], 0, v[156:157]
	v_lshl_add_u64 v[18:19], v[18:19], 0, v[156:157]
	v_lshl_add_u64 v[20:21], v[16:17], 0, v[156:157]
	global_load_dwordx4 v[0:3], v[0:1], off
	s_nop 0
	global_load_dwordx4 v[4:7], v[4:5], off
	s_nop 0
	global_load_dwordx4 v[8:11], v[10:11], off
	s_nop 0
	global_load_dwordx4 v[12:15], v[12:13], off
	s_nop 0
	global_load_dwordx4 v[16:19], v[18:19], off
	s_nop 0
	global_load_dwordx4 v[20:23], v[20:21], off
	s_movk_i32 s10, 0x100
	v_readfirstlane_b32 s18, v100
	v_cmp_gt_i32_e32 vcc, s10, v100
	s_and_saveexec_b64 s[10:11], vcc
	s_cbranch_execz .LBB0_410
	s_lshl_b32 s19, s16, 15
	v_readlane_b32 s20, v252, 3
	s_add_u32 s19, s20, s19
	v_readlane_b32 s20, v252, 4
	s_addc_u32 s20, s20, 0
	s_lshl_b64 s[8:9], s[8:9], 2
	s_add_u32 s8, s19, s8
	s_addc_u32 s9, s20, s9
	v_ashrrev_i32_e32 v101, 31, v100
	v_lshl_add_u64 v[26:27], v[100:101], 2, s[8:9]
	global_load_dword v26, v[26:27], off
	v_lshl_add_u32 v27, v100, 2, 16
	v_add_u32_e32 v27, 0x1b000, v27
	s_waitcnt vmcnt(0)
	ds_write_b32 v27, v26
